# retention scan: q and A fragments in two alternating register sets, requested two chunks ahead; o = gamma*(q.S) + A.v accumulated in one accumulator set
# baseline (speedup 1.0000x reference)
.LBB0_1313:
	s_or_b64 exec, exec, s[0:1]
	s_add_u32 s6, s94, 0x2a402800
	s_addc_u32 s7, s95, 0
	s_cmpk_gt_u32 s2, 0x7f
	s_waitcnt lgkmcnt(0)
	s_barrier
	s_cbranch_scc1 .LBB0_1326
	s_and_b32 s76, s2, 7
	s_lshr_b32 s77, s2, 3
	s_lshr_b32 s78, s77, 3
	s_lshl_b32 s72, s76, 1
	s_add_u32 s72, s72, s78
	s_and_b32 s73, s77, 7
	s_lshr_b32 s74, s72, 2
	s_and_b32 s75, s72, 3
	s_mov_b32 s82, 0xbd020aec
	s_cmp_eq_u32 s75, 1
	s_cselect_b32 s82, 0xbc8102b3, s82
	s_cmp_eq_u32 s75, 2
	s_cselect_b32 s82, 0xbc0080ac, s82
	s_cmp_eq_u32 s75, 3
	s_cselect_b32 s82, 0xbb80402b, s82
	v_lshrrev_b32_e32 v210, 6, v198
	v_and_b32_e32 v211, 15, v198
	v_bfe_u32 v212, v198, 4, 2
	v_readfirstlane_b32 s71, v210
	v_lshl_or_b32 v213, v210, 4, v211
	v_add_u32_e32 v213, 1, v213
	v_cvt_f32_i32_e32 v213, v213
	v_mul_f32_e32 v213, s82, v213
	v_mul_f32_e32 v213, 0x3fb8aa3b, v213
	v_exp_f32_e32 v202, v213
	v_mov_b32_e32 v213, 0x43000000
	v_mul_f32_e32 v213, s82, v213
	v_mul_f32_e32 v213, 0x3fb8aa3b, v213
	v_exp_f32_e32 v204, v213
	s_nop 1
	v_mov_b32_e32 v203, v202
	v_mov_b32_e32 v205, v204
	v_lshlrev_b32_e32 v192, 4, v211
	v_lshl_add_u32 v192, v212, 8, v192
	v_lshlrev_b32_e32 v193, 11, v211
	v_lshl_add_u32 v193, v212, 4, v193
	v_and_b32_e32 v213, 63, v198
	v_lshrrev_b32_e32 v195, 3, v213
	v_and_b32_e32 v215, 7, v213
	v_mul_u32_u24_e32 v214, 144, v195
	v_lshl_add_u32 v215, v215, 4, v214
	v_and_b32_e32 v214, 7, v213
	v_lshlrev_b32_e32 v195, 12, v195
	v_lshl_add_u32 v195, v214, 4, v195
	v_add_u32_e32 v220, 0x8000, v195
	v_mul_u32_u24_e32 v214, 144, v211
	v_lshl_add_u32 v214, v212, 3, v214
	v_mul_u32_u24_e32 v213, 2304, v210
	v_add_u32_e32 v213, 102400, v213
	v_add_u32_e32 v214, v214, v213
	v_add_u32_e32 v215, v215, v213
	v_lshrrev_b32_e32 v213, 3, v198
	v_and_b32_e32 v194, 7, v198
	v_lshlrev_b32_e32 v194, 4, v194
	v_mul_u32_u24_e32 v201, 272, v213
	v_add_u32_e32 v201, v201, v194
	v_lshl_add_u32 v194, v213, 13, v194
	v_add_u32_e32 v201, 67584, v201
	v_mul_u32_u24_e32 v196, 528, v211
	v_lshl_add_u32 v200, v212, 3, v196
	v_lshl_add_u32 v200, v210, 6, v200
	v_add_u32_e32 v200, 33792, v200
	v_lshl_add_u32 v196, v212, 4, v196
	v_mul_u32_u24_e32 v197, 272, v211
	v_lshl_add_u32 v197, v212, 4, v197
	v_add_u32_e32 v197, 67584, v197
	v_lshlrev_b32_e32 v206, 13, v212
	v_lshl_add_u32 v206, v211, 2, v206
	v_add_u32_e32 v207, 2048, v206
	v_add_u32_e32 v208, 4096, v206
	v_add_u32_e32 v209, 6144, v206
	s_mov_b32 s76, 0x27402800
	s_lshl_b32 s77, s72, 20
	s_add_u32 s76, s76, s77
	s_lshl_b32 s77, s71, 12
	s_add_u32 s76, s76, s77
	s_add_u32 s62, s94, s76
	s_addc_u32 s63, s95, 0
	s_mov_b32 s76, 0x28403800
	s_lshl_b32 s77, s72, 21
	s_add_u32 s76, s76, s77
	s_lshl_b32 s77, s71, 13
	s_add_u32 s76, s76, s77
	s_add_u32 s64, s94, s76
	s_addc_u32 s65, s95, 0
	s_mov_b32 s76, 0x1a802800
	s_lshl_b32 s77, s74, 23
	s_add_u32 s76, s76, s77
	s_lshl_b32 s77, s71, 15
	s_add_u32 s76, s76, s77
	s_lshl_b32 s77, s75, 9
	s_add_u32 s76, s76, s77
	s_add_u32 s60, s94, s76
	s_addc_u32 s61, s95, 0
	s_mov_b32 s76, 0x23002800
	s_lshl_b32 s77, s72, 22
	s_add_u32 s76, s76, s77
	s_lshl_b32 s77, s73, 19
	s_add_u32 s76, s76, s77
	s_add_u32 s66, s94, s76
	s_addc_u32 s67, s95, 0
	s_mov_b32 s76, 0x2a402800
	s_lshl_b32 s77, s74, 24
	s_add_u32 s76, s76, s77
	s_lshl_b32 s77, s71, 16
	s_add_u32 s76, s76, s77
	s_lshl_b32 s77, s75, 10
	s_add_u32 s76, s76, s77
	s_lshl_b32 s77, s73, 7
	s_add_u32 s76, s76, s77
	s_add_u32 s68, s94, s76
	s_addc_u32 s69, s95, 0
	s_mov_b32 s76, 0x6500000
	s_lshl_b32 s77, s72, 19
	s_add_u32 s76, s76, s77
	s_lshl_b32 s77, s71, 16
	s_add_u32 s76, s76, s77
	s_lshl_b32 s77, s73, 8
	s_add_u32 s76, s76, s77
	s_add_u32 s44, s92, s76
	s_addc_u32 s45, s93, 0
	s_add_u32 s46, s44, 0x8000
	s_addc_u32 s47, s45, 0
	global_load_dwordx4 v[176:179], v194, s[66:67]
	global_load_dwordx4 v[180:183], v194, s[66:67] offset:128
	global_load_dwordx4 v[0:3], v193, s[60:61]
	global_load_dwordx4 v[4:7], v193, s[60:61] offset:64
	global_load_dwordx4 v[8:11], v193, s[60:61] offset:128
	global_load_dwordx4 v[12:15], v193, s[60:61] offset:192
	global_load_dwordx4 v[16:19], v193, s[60:61] offset:256
	global_load_dwordx4 v[20:23], v193, s[60:61] offset:320
	global_load_dwordx4 v[24:27], v193, s[60:61] offset:384
	global_load_dwordx4 v[28:31], v193, s[60:61] offset:448
	global_load_dwordx4 v[32:35], v192, s[62:63]
	global_load_dwordx4 v[36:39], v192, s[62:63] offset:1024
	global_load_dwordx4 v[40:43], v192, s[62:63] offset:2048
	global_load_dwordx4 v[44:47], v192, s[62:63] offset:3072
	global_load_dwordx4 v[48:51], v192, s[64:65] offset:-4096
	global_load_dwordx4 v[64:67], v192, s[64:65]
	global_load_dwordx4 v[52:55], v192, s[64:65] offset:-3072
	global_load_dwordx4 v[68:71], v192, s[64:65] offset:1024
	global_load_dwordx4 v[56:59], v192, s[64:65] offset:-2048
	global_load_dwordx4 v[72:75], v192, s[64:65] offset:2048
	global_load_dwordx4 v[60:63], v192, s[64:65] offset:-1024
	global_load_dwordx4 v[76:79], v192, s[64:65] offset:3072
	v_mov_b32_e32 v216, 0
	v_mov_b32_e32 v217, 0
	v_mov_b32_e32 v218, 0
	v_mov_b32_e32 v219, 0
	v_mov_b32_e32 v80, 0
	v_mov_b32_e32 v81, 0
	v_mov_b32_e32 v82, 0
	v_mov_b32_e32 v83, 0
	v_mov_b32_e32 v84, 0
	v_mov_b32_e32 v85, 0
	v_mov_b32_e32 v86, 0
	v_mov_b32_e32 v87, 0
	v_mov_b32_e32 v88, 0
	v_mov_b32_e32 v89, 0
	v_mov_b32_e32 v90, 0
	v_mov_b32_e32 v91, 0
	v_mov_b32_e32 v92, 0
	v_mov_b32_e32 v93, 0
	v_mov_b32_e32 v94, 0
	v_mov_b32_e32 v95, 0
	v_mov_b32_e32 v96, 0
	v_mov_b32_e32 v97, 0
	v_mov_b32_e32 v98, 0
	v_mov_b32_e32 v99, 0
	v_mov_b32_e32 v100, 0
	v_mov_b32_e32 v101, 0
	v_mov_b32_e32 v102, 0
	v_mov_b32_e32 v103, 0
	v_mov_b32_e32 v104, 0
	v_mov_b32_e32 v105, 0
	v_mov_b32_e32 v106, 0
	v_mov_b32_e32 v107, 0
	v_mov_b32_e32 v108, 0
	v_mov_b32_e32 v109, 0
	v_mov_b32_e32 v110, 0
	v_mov_b32_e32 v111, 0
	v_lshlrev_b32_e32 v213, 4, v198
	ds_write_b128 v213, v[216:219] offset:0
	ds_write_b128 v213, v[216:219] offset:8192
	ds_write_b128 v213, v[216:219] offset:16384
	ds_write_b128 v213, v[216:219] offset:24576
	ds_write_b128 v213, v[216:219] offset:32768
	s_waitcnt vmcnt(20)
	ds_write_b128 v201, v[176:179]
	ds_write_b128 v201, v[180:183] offset:128
	v_add_u32_e32 v201, 17408, v201
	s_add_u32 s60, s60, 0x40000
	s_addc_u32 s61, s61, 0
	s_add_u32 s62, s62, 0x8000
	s_addc_u32 s63, s63, 0
	s_add_u32 s64, s64, 0x10000
	s_addc_u32 s65, s65, 0
	s_add_u32 s66, s66, 0x100
	s_addc_u32 s67, s67, 0
	global_load_dwordx4 v[230:233], v193, s[60:61]
	global_load_dwordx4 v[234:237], v193, s[60:61] offset:64
	global_load_dwordx4 v[238:241], v193, s[60:61] offset:128
	global_load_dwordx4 v[242:245], v193, s[60:61] offset:192
	global_load_dwordx4 v[246:249], v193, s[60:61] offset:256
	global_load_dwordx4 v[250:253], v193, s[60:61] offset:320
	global_load_dwordx4 v[184:187], v193, s[60:61] offset:384
	global_load_dwordx4 v[188:191], v193, s[60:61] offset:448
	global_load_dwordx4 v[128:131], v192, s[62:63]
	global_load_dwordx4 v[132:135], v192, s[62:63] offset:1024
	global_load_dwordx4 v[136:139], v192, s[62:63] offset:2048
	global_load_dwordx4 v[140:143], v192, s[62:63] offset:3072
	s_add_u32 s60, s60, 0x40000
	s_addc_u32 s61, s61, 0
	s_add_u32 s62, s62, 0x8000
	s_addc_u32 s63, s63, 0
	global_load_dwordx4 v[222:225], v194, s[66:67]
	global_load_dwordx4 v[226:229], v194, s[66:67] offset:128
	s_add_u32 s66, s66, 0x100
	s_addc_u32 s67, s67, 0
	s_mov_b32 s70, 0
	s_mov_b32 s80, 33792
	s_mov_b32 s81, 17408
	s_waitcnt vmcnt(0) lgkmcnt(0)
	s_barrier
.Lscan_chunk:
	global_load_dwordx4 v[176:179], v194, s[66:67]
	global_load_dwordx4 v[180:183], v194, s[66:67] offset:128
	ds_read_b128 v[144:147], v196 offset:0
	ds_read_b128 v[148:151], v196 offset:8448
	ds_read_b128 v[152:155], v196 offset:16896
	ds_read_b128 v[156:159], v196 offset:25344
	ds_read_b128 v[160:163], v196 offset:64
	ds_read_b128 v[164:167], v196 offset:8512
	ds_read_b128 v[168:171], v196 offset:16960
	s_waitcnt lgkmcnt(6)
	s_waitcnt vmcnt(47)
	v_mfma_f32_16x16x32_bf16 v[112:115], v[144:147], v[0:3], 0
	ds_read_b128 v[172:175], v196 offset:25408
	s_waitcnt lgkmcnt(6)
	v_mfma_f32_16x16x32_bf16 v[116:119], v[148:151], v[0:3], 0
	ds_read_b128 v[144:147], v196 offset:128
	s_waitcnt lgkmcnt(6)
	v_mfma_f32_16x16x32_bf16 v[120:123], v[152:155], v[0:3], 0
	ds_read_b128 v[148:151], v196 offset:8576
	s_waitcnt lgkmcnt(6)
	v_mfma_f32_16x16x32_bf16 v[124:127], v[156:159], v[0:3], 0
	global_load_dwordx4 v[0:3], v193, s[60:61]
	ds_read_b128 v[152:155], v196 offset:17024
	s_waitcnt lgkmcnt(6)
	s_waitcnt vmcnt(47)
	v_mfma_f32_16x16x32_bf16 v[112:115], v[160:163], v[4:7], v[112:115]
	ds_read_b128 v[156:159], v196 offset:25472
	s_waitcnt lgkmcnt(6)
	v_mfma_f32_16x16x32_bf16 v[116:119], v[164:167], v[4:7], v[116:119]
	ds_read_b128 v[160:163], v196 offset:192
	s_waitcnt lgkmcnt(6)
	v_mfma_f32_16x16x32_bf16 v[120:123], v[168:171], v[4:7], v[120:123]
	ds_read_b128 v[164:167], v196 offset:8640
	s_waitcnt lgkmcnt(6)
	v_mfma_f32_16x16x32_bf16 v[124:127], v[172:175], v[4:7], v[124:127]
	global_load_dwordx4 v[4:7], v193, s[60:61] offset:64
	ds_read_b128 v[168:171], v196 offset:17088
	s_waitcnt lgkmcnt(6)
	s_waitcnt vmcnt(47)
	v_mfma_f32_16x16x32_bf16 v[112:115], v[144:147], v[8:11], v[112:115]
	ds_read_b128 v[172:175], v196 offset:25536
	s_waitcnt lgkmcnt(6)
	v_mfma_f32_16x16x32_bf16 v[116:119], v[148:151], v[8:11], v[116:119]
	ds_read_b128 v[144:147], v196 offset:256
	s_waitcnt lgkmcnt(6)
	v_mfma_f32_16x16x32_bf16 v[120:123], v[152:155], v[8:11], v[120:123]
	ds_read_b128 v[148:151], v196 offset:8704
	s_waitcnt lgkmcnt(6)
	v_mfma_f32_16x16x32_bf16 v[124:127], v[156:159], v[8:11], v[124:127]
	global_load_dwordx4 v[8:11], v193, s[60:61] offset:128
	ds_read_b128 v[152:155], v196 offset:17152
	s_waitcnt lgkmcnt(6)
	s_waitcnt vmcnt(47)
	v_mfma_f32_16x16x32_bf16 v[112:115], v[160:163], v[12:15], v[112:115]
	ds_read_b128 v[156:159], v196 offset:25600
	s_waitcnt lgkmcnt(6)
	v_mfma_f32_16x16x32_bf16 v[116:119], v[164:167], v[12:15], v[116:119]
	ds_read_b128 v[160:163], v196 offset:320
	s_waitcnt lgkmcnt(6)
	v_mfma_f32_16x16x32_bf16 v[120:123], v[168:171], v[12:15], v[120:123]
	ds_read_b128 v[164:167], v196 offset:8768
	s_waitcnt lgkmcnt(6)
	v_mfma_f32_16x16x32_bf16 v[124:127], v[172:175], v[12:15], v[124:127]
	global_load_dwordx4 v[12:15], v193, s[60:61] offset:192
	ds_read_b128 v[168:171], v196 offset:17216
	s_waitcnt lgkmcnt(6)
	s_waitcnt vmcnt(47)
	v_mfma_f32_16x16x32_bf16 v[112:115], v[144:147], v[16:19], v[112:115]
	ds_read_b128 v[172:175], v196 offset:25664
	s_waitcnt lgkmcnt(6)
	v_mfma_f32_16x16x32_bf16 v[116:119], v[148:151], v[16:19], v[116:119]
	ds_read_b128 v[144:147], v196 offset:384
	s_waitcnt lgkmcnt(6)
	v_mfma_f32_16x16x32_bf16 v[120:123], v[152:155], v[16:19], v[120:123]
	ds_read_b128 v[148:151], v196 offset:8832
	s_waitcnt lgkmcnt(6)
	v_mfma_f32_16x16x32_bf16 v[124:127], v[156:159], v[16:19], v[124:127]
	global_load_dwordx4 v[16:19], v193, s[60:61] offset:256
	ds_read_b128 v[152:155], v196 offset:17280
	s_waitcnt lgkmcnt(6)
	s_waitcnt vmcnt(47)
	v_mfma_f32_16x16x32_bf16 v[112:115], v[160:163], v[20:23], v[112:115]
	ds_read_b128 v[156:159], v196 offset:25728
	s_waitcnt lgkmcnt(6)
	v_mfma_f32_16x16x32_bf16 v[116:119], v[164:167], v[20:23], v[116:119]
	ds_read_b128 v[160:163], v196 offset:448
	s_waitcnt lgkmcnt(6)
	v_mfma_f32_16x16x32_bf16 v[120:123], v[168:171], v[20:23], v[120:123]
	ds_read_b128 v[164:167], v196 offset:8896
	s_waitcnt lgkmcnt(6)
	v_mfma_f32_16x16x32_bf16 v[124:127], v[172:175], v[20:23], v[124:127]
	global_load_dwordx4 v[20:23], v193, s[60:61] offset:320
	ds_read_b128 v[168:171], v196 offset:17344
	s_waitcnt lgkmcnt(6)
	s_waitcnt vmcnt(47)
	v_mfma_f32_16x16x32_bf16 v[112:115], v[144:147], v[24:27], v[112:115]
	ds_read_b128 v[172:175], v196 offset:25792
	s_waitcnt lgkmcnt(6)
	v_mfma_f32_16x16x32_bf16 v[116:119], v[148:151], v[24:27], v[116:119]
	s_waitcnt lgkmcnt(5)
	v_mfma_f32_16x16x32_bf16 v[120:123], v[152:155], v[24:27], v[120:123]
	s_waitcnt lgkmcnt(4)
	v_mfma_f32_16x16x32_bf16 v[124:127], v[156:159], v[24:27], v[124:127]
	global_load_dwordx4 v[24:27], v193, s[60:61] offset:384
	s_waitcnt lgkmcnt(3)
	s_waitcnt vmcnt(47)
	v_mfma_f32_16x16x32_bf16 v[112:115], v[160:163], v[28:31], v[112:115]
	s_waitcnt lgkmcnt(2)
	v_mfma_f32_16x16x32_bf16 v[116:119], v[164:167], v[28:31], v[116:119]
	s_waitcnt lgkmcnt(1)
	v_mfma_f32_16x16x32_bf16 v[120:123], v[168:171], v[28:31], v[120:123]
	s_waitcnt lgkmcnt(0)
	v_mfma_f32_16x16x32_bf16 v[124:127], v[172:175], v[28:31], v[124:127]
	global_load_dwordx4 v[28:31], v193, s[60:61] offset:448
	s_nop 7
	v_pk_mul_f32 v[112:113], v[112:113], v[202:203]
	v_pk_mul_f32 v[114:115], v[114:115], v[202:203]
	v_pk_mul_f32 v[116:117], v[116:117], v[202:203]
	v_pk_mul_f32 v[118:119], v[118:119], v[202:203]
	v_pk_mul_f32 v[120:121], v[120:121], v[202:203]
	v_pk_mul_f32 v[122:123], v[122:123], v[202:203]
	v_pk_mul_f32 v[124:125], v[124:125], v[202:203]
	v_pk_mul_f32 v[126:127], v[126:127], v[202:203]
	ds_read_b128 v[144:147], v197 offset:0
	ds_read_b128 v[148:151], v197 offset:4352
	ds_read_b128 v[152:155], v197 offset:8704
	ds_read_b128 v[156:159], v197 offset:13056
	ds_read_b128 v[160:163], v197 offset:64
	ds_read_b128 v[164:167], v197 offset:4416
	ds_read_b128 v[168:171], v197 offset:8768
	s_waitcnt lgkmcnt(6)
	s_waitcnt vmcnt(47)
	v_mfma_f32_16x16x32_bf16 v[112:115], v[144:147], v[32:35], v[112:115]
	ds_read_b128 v[172:175], v197 offset:13120
	s_waitcnt lgkmcnt(6)
	v_mfma_f32_16x16x32_bf16 v[116:119], v[148:151], v[32:35], v[116:119]
	ds_read_b128 v[144:147], v197 offset:128
	s_waitcnt lgkmcnt(6)
	v_mfma_f32_16x16x32_bf16 v[120:123], v[152:155], v[32:35], v[120:123]
	ds_read_b128 v[148:151], v197 offset:4480
	s_waitcnt lgkmcnt(6)
	v_mfma_f32_16x16x32_bf16 v[124:127], v[156:159], v[32:35], v[124:127]
	global_load_dwordx4 v[32:35], v192, s[62:63]
	ds_read_b128 v[152:155], v197 offset:8832
	s_waitcnt lgkmcnt(6)
	s_waitcnt vmcnt(47)
	v_mfma_f32_16x16x32_bf16 v[112:115], v[160:163], v[36:39], v[112:115]
	ds_read_b128 v[156:159], v197 offset:13184
	s_waitcnt lgkmcnt(6)
	v_mfma_f32_16x16x32_bf16 v[116:119], v[164:167], v[36:39], v[116:119]
	ds_read_b128 v[160:163], v197 offset:192
	s_waitcnt lgkmcnt(6)
	v_mfma_f32_16x16x32_bf16 v[120:123], v[168:171], v[36:39], v[120:123]
	ds_read_b128 v[164:167], v197 offset:4544
	s_waitcnt lgkmcnt(6)
	v_mfma_f32_16x16x32_bf16 v[124:127], v[172:175], v[36:39], v[124:127]
	global_load_dwordx4 v[36:39], v192, s[62:63] offset:1024
	ds_read_b128 v[168:171], v197 offset:8896
	s_waitcnt lgkmcnt(6)
	s_waitcnt vmcnt(47)
	v_mfma_f32_16x16x32_bf16 v[112:115], v[144:147], v[40:43], v[112:115]
	ds_read_b128 v[172:175], v197 offset:13248
	s_waitcnt lgkmcnt(6)
	v_mfma_f32_16x16x32_bf16 v[116:119], v[148:151], v[40:43], v[116:119]
	s_waitcnt lgkmcnt(5)
	v_mfma_f32_16x16x32_bf16 v[120:123], v[152:155], v[40:43], v[120:123]
	s_waitcnt lgkmcnt(4)
	v_mfma_f32_16x16x32_bf16 v[124:127], v[156:159], v[40:43], v[124:127]
	global_load_dwordx4 v[40:43], v192, s[62:63] offset:2048
	s_waitcnt lgkmcnt(3)
	s_waitcnt vmcnt(47)
	v_mfma_f32_16x16x32_bf16 v[112:115], v[160:163], v[44:47], v[112:115]
	s_waitcnt lgkmcnt(2)
	v_mfma_f32_16x16x32_bf16 v[116:119], v[164:167], v[44:47], v[116:119]
	s_waitcnt lgkmcnt(1)
	v_mfma_f32_16x16x32_bf16 v[120:123], v[168:171], v[44:47], v[120:123]
	s_waitcnt lgkmcnt(0)
	v_mfma_f32_16x16x32_bf16 v[124:127], v[172:175], v[44:47], v[124:127]
	global_load_dwordx4 v[44:47], v192, s[62:63] offset:3072
	s_nop 7
	v_cvt_pk_bf16_f32 v160, v112, v113
	v_cvt_pk_bf16_f32 v161, v114, v115
	v_cvt_pk_bf16_f32 v162, v116, v117
	v_cvt_pk_bf16_f32 v163, v118, v119
	v_cvt_pk_bf16_f32 v164, v120, v121
	v_cvt_pk_bf16_f32 v165, v122, v123
	v_cvt_pk_bf16_f32 v166, v124, v125
	v_cvt_pk_bf16_f32 v167, v126, v127
	ds_write_b64 v214, v[160:161]
	ds_write_b64 v214, v[162:163] offset:32
	ds_write_b64 v214, v[164:165] offset:64
	ds_write_b64 v214, v[166:167] offset:96
	s_waitcnt lgkmcnt(0)
	ds_read_b128 v[144:147], v215
	ds_read_b128 v[148:151], v215 offset:1152
	s_waitcnt lgkmcnt(0)
	global_store_dwordx4 v195, v[144:147], s[68:69]
	global_store_dwordx4 v220, v[148:151], s[68:69]
	v_pk_mul_f32 v[80:81], v[80:81], v[204:205]
	v_pk_mul_f32 v[82:83], v[82:83], v[204:205]
	v_pk_mul_f32 v[84:85], v[84:85], v[204:205]
	v_pk_mul_f32 v[86:87], v[86:87], v[204:205]
	v_pk_mul_f32 v[88:89], v[88:89], v[204:205]
	v_pk_mul_f32 v[90:91], v[90:91], v[204:205]
	v_pk_mul_f32 v[92:93], v[92:93], v[204:205]
	v_pk_mul_f32 v[94:95], v[94:95], v[204:205]
	v_pk_mul_f32 v[96:97], v[96:97], v[204:205]
	v_pk_mul_f32 v[98:99], v[98:99], v[204:205]
	v_pk_mul_f32 v[100:101], v[100:101], v[204:205]
	v_pk_mul_f32 v[102:103], v[102:103], v[204:205]
	v_pk_mul_f32 v[104:105], v[104:105], v[204:205]
	v_pk_mul_f32 v[106:107], v[106:107], v[204:205]
	v_pk_mul_f32 v[108:109], v[108:109], v[204:205]
	v_pk_mul_f32 v[110:111], v[110:111], v[204:205]
	ds_read_b128 v[144:147], v197 offset:0
	ds_read_b128 v[148:151], v197 offset:4352
	ds_read_b128 v[152:155], v197 offset:8704
	ds_read_b128 v[156:159], v197 offset:13056
	ds_read_b128 v[160:163], v197 offset:64
	ds_read_b128 v[164:167], v197 offset:4416
	ds_read_b128 v[168:171], v197 offset:8768
	s_waitcnt lgkmcnt(6)
	s_waitcnt vmcnt(22)
	v_mfma_f32_16x16x32_bf16 v[80:83], v[48:51], v[144:147], v[80:83]
	v_mfma_f32_16x16x32_bf16 v[96:99], v[64:67], v[144:147], v[96:99]
	ds_read_b128 v[172:175], v197 offset:13120
	s_waitcnt lgkmcnt(6)
	v_mfma_f32_16x16x32_bf16 v[84:87], v[48:51], v[148:151], v[84:87]
	v_mfma_f32_16x16x32_bf16 v[100:103], v[64:67], v[148:151], v[100:103]
	ds_read_b128 v[144:147], v197 offset:128
	s_waitcnt lgkmcnt(6)
	v_mfma_f32_16x16x32_bf16 v[88:91], v[48:51], v[152:155], v[88:91]
	v_mfma_f32_16x16x32_bf16 v[104:107], v[64:67], v[152:155], v[104:107]
	ds_read_b128 v[148:151], v197 offset:4480
	s_waitcnt lgkmcnt(6)
	v_mfma_f32_16x16x32_bf16 v[92:95], v[48:51], v[156:159], v[92:95]
	v_mfma_f32_16x16x32_bf16 v[108:111], v[64:67], v[156:159], v[108:111]
	global_load_dwordx4 v[48:51], v192, s[64:65] offset:-4096
	global_load_dwordx4 v[64:67], v192, s[64:65]
	ds_read_b128 v[152:155], v197 offset:8832
	s_waitcnt lgkmcnt(6)
	s_waitcnt vmcnt(22)
	v_mfma_f32_16x16x32_bf16 v[80:83], v[52:55], v[160:163], v[80:83]
	v_mfma_f32_16x16x32_bf16 v[96:99], v[68:71], v[160:163], v[96:99]
	ds_read_b128 v[156:159], v197 offset:13184
	s_waitcnt lgkmcnt(6)
	v_mfma_f32_16x16x32_bf16 v[84:87], v[52:55], v[164:167], v[84:87]
	v_mfma_f32_16x16x32_bf16 v[100:103], v[68:71], v[164:167], v[100:103]
	ds_read_b128 v[160:163], v197 offset:192
	s_waitcnt lgkmcnt(6)
	v_mfma_f32_16x16x32_bf16 v[88:91], v[52:55], v[168:171], v[88:91]
	v_mfma_f32_16x16x32_bf16 v[104:107], v[68:71], v[168:171], v[104:107]
	ds_read_b128 v[164:167], v197 offset:4544
	s_waitcnt lgkmcnt(6)
	v_mfma_f32_16x16x32_bf16 v[92:95], v[52:55], v[172:175], v[92:95]
	v_mfma_f32_16x16x32_bf16 v[108:111], v[68:71], v[172:175], v[108:111]
	global_load_dwordx4 v[52:55], v192, s[64:65] offset:-3072
	global_load_dwordx4 v[68:71], v192, s[64:65] offset:1024
	ds_read_b128 v[168:171], v197 offset:8896
	s_waitcnt lgkmcnt(6)
	s_waitcnt vmcnt(22)
	v_mfma_f32_16x16x32_bf16 v[80:83], v[56:59], v[144:147], v[80:83]
	v_mfma_f32_16x16x32_bf16 v[96:99], v[72:75], v[144:147], v[96:99]
	ds_read_b128 v[172:175], v197 offset:13248
	s_waitcnt lgkmcnt(6)
	v_mfma_f32_16x16x32_bf16 v[84:87], v[56:59], v[148:151], v[84:87]
	v_mfma_f32_16x16x32_bf16 v[100:103], v[72:75], v[148:151], v[100:103]
	s_waitcnt lgkmcnt(5)
	v_mfma_f32_16x16x32_bf16 v[88:91], v[56:59], v[152:155], v[88:91]
	v_mfma_f32_16x16x32_bf16 v[104:107], v[72:75], v[152:155], v[104:107]
	s_waitcnt lgkmcnt(4)
	v_mfma_f32_16x16x32_bf16 v[92:95], v[56:59], v[156:159], v[92:95]
	v_mfma_f32_16x16x32_bf16 v[108:111], v[72:75], v[156:159], v[108:111]
	global_load_dwordx4 v[56:59], v192, s[64:65] offset:-2048
	global_load_dwordx4 v[72:75], v192, s[64:65] offset:2048
	s_waitcnt lgkmcnt(3)
	s_waitcnt vmcnt(22)
	v_mfma_f32_16x16x32_bf16 v[80:83], v[60:63], v[160:163], v[80:83]
	v_mfma_f32_16x16x32_bf16 v[96:99], v[76:79], v[160:163], v[96:99]
	s_waitcnt lgkmcnt(2)
	v_mfma_f32_16x16x32_bf16 v[84:87], v[60:63], v[164:167], v[84:87]
	v_mfma_f32_16x16x32_bf16 v[100:103], v[76:79], v[164:167], v[100:103]
	s_waitcnt lgkmcnt(1)
	v_mfma_f32_16x16x32_bf16 v[88:91], v[60:63], v[168:171], v[88:91]
	v_mfma_f32_16x16x32_bf16 v[104:107], v[76:79], v[168:171], v[104:107]
	s_waitcnt lgkmcnt(0)
	v_mfma_f32_16x16x32_bf16 v[92:95], v[60:63], v[172:175], v[92:95]
	v_mfma_f32_16x16x32_bf16 v[108:111], v[76:79], v[172:175], v[108:111]
	global_load_dwordx4 v[60:63], v192, s[64:65] offset:-1024
	global_load_dwordx4 v[76:79], v192, s[64:65] offset:3072
	s_nop 7
	v_cvt_pk_bf16_f32 v144, v80, v81
	v_cvt_pk_bf16_f32 v145, v82, v83
	ds_write_b64 v200, v[144:145] offset:0
	v_cvt_pk_bf16_f32 v148, v84, v85
	v_cvt_pk_bf16_f32 v149, v86, v87
	ds_write_b64 v200, v[148:149] offset:8448
	v_cvt_pk_bf16_f32 v152, v88, v89
	v_cvt_pk_bf16_f32 v153, v90, v91
	ds_write_b64 v200, v[152:153] offset:16896
	v_cvt_pk_bf16_f32 v156, v92, v93
	v_cvt_pk_bf16_f32 v157, v94, v95
	ds_write_b64 v200, v[156:157] offset:25344
	v_cvt_pk_bf16_f32 v160, v96, v97
	v_cvt_pk_bf16_f32 v161, v98, v99
	ds_write_b64 v200, v[160:161] offset:32
	v_cvt_pk_bf16_f32 v164, v100, v101
	v_cvt_pk_bf16_f32 v165, v102, v103
	ds_write_b64 v200, v[164:165] offset:8480
	v_cvt_pk_bf16_f32 v168, v104, v105
	v_cvt_pk_bf16_f32 v169, v106, v107
	ds_write_b64 v200, v[168:169] offset:16928
	v_cvt_pk_bf16_f32 v172, v108, v109
	v_cvt_pk_bf16_f32 v173, v110, v111
	ds_write_b64 v200, v[172:173] offset:25376
	s_waitcnt vmcnt(46)
	ds_write_b128 v201, v[222:225]
	ds_write_b128 v201, v[226:229] offset:128
	v_add_u32_e32 v196, s80, v196
	v_subrev_u32_e32 v200, s80, v200
	v_add_u32_e32 v197, s81, v197
	v_subrev_u32_e32 v201, s81, v201
	s_sub_u32 s80, 0, s80
	s_sub_u32 s81, 0, s81
	s_add_u32 s68, s68, 0x80000
	s_addc_u32 s69, s69, 0
	s_add_u32 s70, s70, 1
	s_cmp_lt_u32 s70, 31
	s_cselect_b32 s83, 1, 0
	s_lshl_b32 s76, s83, 16
	s_add_u32 s64, s64, s76
	s_addc_u32 s65, s65, 0
	s_cmp_lt_u32 s70, 30
	s_cselect_b32 s83, 1, 0
	s_lshl_b32 s76, s83, 18
	s_add_u32 s60, s60, s76
	s_addc_u32 s61, s61, 0
	s_lshl_b32 s76, s83, 15
	s_add_u32 s62, s62, s76
	s_addc_u32 s63, s63, 0
	s_lshl_b32 s76, s83, 8
	s_add_u32 s66, s66, s76
	s_addc_u32 s67, s67, 0
	s_waitcnt lgkmcnt(0)
	s_barrier
	global_load_dwordx4 v[222:225], v194, s[66:67]
	global_load_dwordx4 v[226:229], v194, s[66:67] offset:128
	ds_read_b128 v[144:147], v196 offset:0
	ds_read_b128 v[148:151], v196 offset:8448
	ds_read_b128 v[152:155], v196 offset:16896
	ds_read_b128 v[156:159], v196 offset:25344
	ds_read_b128 v[160:163], v196 offset:64
	ds_read_b128 v[164:167], v196 offset:8512
	ds_read_b128 v[168:171], v196 offset:16960
	s_waitcnt lgkmcnt(6)
	s_waitcnt vmcnt(47)
	v_mfma_f32_16x16x32_bf16 v[112:115], v[144:147], v[230:233], 0
	ds_read_b128 v[172:175], v196 offset:25408
	s_waitcnt lgkmcnt(6)
	v_mfma_f32_16x16x32_bf16 v[116:119], v[148:151], v[230:233], 0
	ds_read_b128 v[144:147], v196 offset:128
	s_waitcnt lgkmcnt(6)
	v_mfma_f32_16x16x32_bf16 v[120:123], v[152:155], v[230:233], 0
	ds_read_b128 v[148:151], v196 offset:8576
	s_waitcnt lgkmcnt(6)
	v_mfma_f32_16x16x32_bf16 v[124:127], v[156:159], v[230:233], 0
	global_load_dwordx4 v[230:233], v193, s[60:61]
	ds_read_b128 v[152:155], v196 offset:17024
	s_waitcnt lgkmcnt(6)
	s_waitcnt vmcnt(47)
	v_mfma_f32_16x16x32_bf16 v[112:115], v[160:163], v[234:237], v[112:115]
	ds_read_b128 v[156:159], v196 offset:25472
	s_waitcnt lgkmcnt(6)
	v_mfma_f32_16x16x32_bf16 v[116:119], v[164:167], v[234:237], v[116:119]
	ds_read_b128 v[160:163], v196 offset:192
	s_waitcnt lgkmcnt(6)
	v_mfma_f32_16x16x32_bf16 v[120:123], v[168:171], v[234:237], v[120:123]
	ds_read_b128 v[164:167], v196 offset:8640
	s_waitcnt lgkmcnt(6)
	v_mfma_f32_16x16x32_bf16 v[124:127], v[172:175], v[234:237], v[124:127]
	global_load_dwordx4 v[234:237], v193, s[60:61] offset:64
	ds_read_b128 v[168:171], v196 offset:17088
	s_waitcnt lgkmcnt(6)
	s_waitcnt vmcnt(47)
	v_mfma_f32_16x16x32_bf16 v[112:115], v[144:147], v[238:241], v[112:115]
	ds_read_b128 v[172:175], v196 offset:25536
	s_waitcnt lgkmcnt(6)
	v_mfma_f32_16x16x32_bf16 v[116:119], v[148:151], v[238:241], v[116:119]
	ds_read_b128 v[144:147], v196 offset:256
	s_waitcnt lgkmcnt(6)
	v_mfma_f32_16x16x32_bf16 v[120:123], v[152:155], v[238:241], v[120:123]
	ds_read_b128 v[148:151], v196 offset:8704
	s_waitcnt lgkmcnt(6)
	v_mfma_f32_16x16x32_bf16 v[124:127], v[156:159], v[238:241], v[124:127]
	global_load_dwordx4 v[238:241], v193, s[60:61] offset:128
	ds_read_b128 v[152:155], v196 offset:17152
	s_waitcnt lgkmcnt(6)
	s_waitcnt vmcnt(47)
	v_mfma_f32_16x16x32_bf16 v[112:115], v[160:163], v[242:245], v[112:115]
	ds_read_b128 v[156:159], v196 offset:25600
	s_waitcnt lgkmcnt(6)
	v_mfma_f32_16x16x32_bf16 v[116:119], v[164:167], v[242:245], v[116:119]
	ds_read_b128 v[160:163], v196 offset:320
	s_waitcnt lgkmcnt(6)
	v_mfma_f32_16x16x32_bf16 v[120:123], v[168:171], v[242:245], v[120:123]
	ds_read_b128 v[164:167], v196 offset:8768
	s_waitcnt lgkmcnt(6)
	v_mfma_f32_16x16x32_bf16 v[124:127], v[172:175], v[242:245], v[124:127]
	global_load_dwordx4 v[242:245], v193, s[60:61] offset:192
	ds_read_b128 v[168:171], v196 offset:17216
	s_waitcnt lgkmcnt(6)
	s_waitcnt vmcnt(47)
	v_mfma_f32_16x16x32_bf16 v[112:115], v[144:147], v[246:249], v[112:115]
	ds_read_b128 v[172:175], v196 offset:25664
	s_waitcnt lgkmcnt(6)
	v_mfma_f32_16x16x32_bf16 v[116:119], v[148:151], v[246:249], v[116:119]
	ds_read_b128 v[144:147], v196 offset:384
	s_waitcnt lgkmcnt(6)
	v_mfma_f32_16x16x32_bf16 v[120:123], v[152:155], v[246:249], v[120:123]
	ds_read_b128 v[148:151], v196 offset:8832
	s_waitcnt lgkmcnt(6)
	v_mfma_f32_16x16x32_bf16 v[124:127], v[156:159], v[246:249], v[124:127]
	global_load_dwordx4 v[246:249], v193, s[60:61] offset:256
	ds_read_b128 v[152:155], v196 offset:17280
	s_waitcnt lgkmcnt(6)
	s_waitcnt vmcnt(47)
	v_mfma_f32_16x16x32_bf16 v[112:115], v[160:163], v[250:253], v[112:115]
	ds_read_b128 v[156:159], v196 offset:25728
	s_waitcnt lgkmcnt(6)
	v_mfma_f32_16x16x32_bf16 v[116:119], v[164:167], v[250:253], v[116:119]
	ds_read_b128 v[160:163], v196 offset:448
	s_waitcnt lgkmcnt(6)
	v_mfma_f32_16x16x32_bf16 v[120:123], v[168:171], v[250:253], v[120:123]
	ds_read_b128 v[164:167], v196 offset:8896
	s_waitcnt lgkmcnt(6)
	v_mfma_f32_16x16x32_bf16 v[124:127], v[172:175], v[250:253], v[124:127]
	global_load_dwordx4 v[250:253], v193, s[60:61] offset:320
	ds_read_b128 v[168:171], v196 offset:17344
	s_waitcnt lgkmcnt(6)
	s_waitcnt vmcnt(47)
	v_mfma_f32_16x16x32_bf16 v[112:115], v[144:147], v[184:187], v[112:115]
	ds_read_b128 v[172:175], v196 offset:25792
	s_waitcnt lgkmcnt(6)
	v_mfma_f32_16x16x32_bf16 v[116:119], v[148:151], v[184:187], v[116:119]
	s_waitcnt lgkmcnt(5)
	v_mfma_f32_16x16x32_bf16 v[120:123], v[152:155], v[184:187], v[120:123]
	s_waitcnt lgkmcnt(4)
	v_mfma_f32_16x16x32_bf16 v[124:127], v[156:159], v[184:187], v[124:127]
	global_load_dwordx4 v[184:187], v193, s[60:61] offset:384
	s_waitcnt lgkmcnt(3)
	s_waitcnt vmcnt(47)
	v_mfma_f32_16x16x32_bf16 v[112:115], v[160:163], v[188:191], v[112:115]
	s_waitcnt lgkmcnt(2)
	v_mfma_f32_16x16x32_bf16 v[116:119], v[164:167], v[188:191], v[116:119]
	s_waitcnt lgkmcnt(1)
	v_mfma_f32_16x16x32_bf16 v[120:123], v[168:171], v[188:191], v[120:123]
	s_waitcnt lgkmcnt(0)
	v_mfma_f32_16x16x32_bf16 v[124:127], v[172:175], v[188:191], v[124:127]
	global_load_dwordx4 v[188:191], v193, s[60:61] offset:448
	s_nop 7
	v_pk_mul_f32 v[112:113], v[112:113], v[202:203]
	v_pk_mul_f32 v[114:115], v[114:115], v[202:203]
	v_pk_mul_f32 v[116:117], v[116:117], v[202:203]
	v_pk_mul_f32 v[118:119], v[118:119], v[202:203]
	v_pk_mul_f32 v[120:121], v[120:121], v[202:203]
	v_pk_mul_f32 v[122:123], v[122:123], v[202:203]
	v_pk_mul_f32 v[124:125], v[124:125], v[202:203]
	v_pk_mul_f32 v[126:127], v[126:127], v[202:203]
	ds_read_b128 v[144:147], v197 offset:0
	ds_read_b128 v[148:151], v197 offset:4352
	ds_read_b128 v[152:155], v197 offset:8704
	ds_read_b128 v[156:159], v197 offset:13056
	ds_read_b128 v[160:163], v197 offset:64
	ds_read_b128 v[164:167], v197 offset:4416
	ds_read_b128 v[168:171], v197 offset:8768
	s_waitcnt lgkmcnt(6)
	s_waitcnt vmcnt(47)
	v_mfma_f32_16x16x32_bf16 v[112:115], v[144:147], v[128:131], v[112:115]
	ds_read_b128 v[172:175], v197 offset:13120
	s_waitcnt lgkmcnt(6)
	v_mfma_f32_16x16x32_bf16 v[116:119], v[148:151], v[128:131], v[116:119]
	ds_read_b128 v[144:147], v197 offset:128
	s_waitcnt lgkmcnt(6)
	v_mfma_f32_16x16x32_bf16 v[120:123], v[152:155], v[128:131], v[120:123]
	ds_read_b128 v[148:151], v197 offset:4480
	s_waitcnt lgkmcnt(6)
	v_mfma_f32_16x16x32_bf16 v[124:127], v[156:159], v[128:131], v[124:127]
	global_load_dwordx4 v[128:131], v192, s[62:63]
	ds_read_b128 v[152:155], v197 offset:8832
	s_waitcnt lgkmcnt(6)
	s_waitcnt vmcnt(47)
	v_mfma_f32_16x16x32_bf16 v[112:115], v[160:163], v[132:135], v[112:115]
	ds_read_b128 v[156:159], v197 offset:13184
	s_waitcnt lgkmcnt(6)
	v_mfma_f32_16x16x32_bf16 v[116:119], v[164:167], v[132:135], v[116:119]
	ds_read_b128 v[160:163], v197 offset:192
	s_waitcnt lgkmcnt(6)
	v_mfma_f32_16x16x32_bf16 v[120:123], v[168:171], v[132:135], v[120:123]
	ds_read_b128 v[164:167], v197 offset:4544
	s_waitcnt lgkmcnt(6)
	v_mfma_f32_16x16x32_bf16 v[124:127], v[172:175], v[132:135], v[124:127]
	global_load_dwordx4 v[132:135], v192, s[62:63] offset:1024
	ds_read_b128 v[168:171], v197 offset:8896
	s_waitcnt lgkmcnt(6)
	s_waitcnt vmcnt(47)
	v_mfma_f32_16x16x32_bf16 v[112:115], v[144:147], v[136:139], v[112:115]
	ds_read_b128 v[172:175], v197 offset:13248
	s_waitcnt lgkmcnt(6)
	v_mfma_f32_16x16x32_bf16 v[116:119], v[148:151], v[136:139], v[116:119]
	s_waitcnt lgkmcnt(5)
	v_mfma_f32_16x16x32_bf16 v[120:123], v[152:155], v[136:139], v[120:123]
	s_waitcnt lgkmcnt(4)
	v_mfma_f32_16x16x32_bf16 v[124:127], v[156:159], v[136:139], v[124:127]
	global_load_dwordx4 v[136:139], v192, s[62:63] offset:2048
	s_waitcnt lgkmcnt(3)
	s_waitcnt vmcnt(47)
	v_mfma_f32_16x16x32_bf16 v[112:115], v[160:163], v[140:143], v[112:115]
	s_waitcnt lgkmcnt(2)
	v_mfma_f32_16x16x32_bf16 v[116:119], v[164:167], v[140:143], v[116:119]
	s_waitcnt lgkmcnt(1)
	v_mfma_f32_16x16x32_bf16 v[120:123], v[168:171], v[140:143], v[120:123]
	s_waitcnt lgkmcnt(0)
	v_mfma_f32_16x16x32_bf16 v[124:127], v[172:175], v[140:143], v[124:127]
	global_load_dwordx4 v[140:143], v192, s[62:63] offset:3072
	s_nop 7
	v_cvt_pk_bf16_f32 v160, v112, v113
	v_cvt_pk_bf16_f32 v161, v114, v115
	v_cvt_pk_bf16_f32 v162, v116, v117
	v_cvt_pk_bf16_f32 v163, v118, v119
	v_cvt_pk_bf16_f32 v164, v120, v121
	v_cvt_pk_bf16_f32 v165, v122, v123
	v_cvt_pk_bf16_f32 v166, v124, v125
	v_cvt_pk_bf16_f32 v167, v126, v127
	ds_write_b64 v214, v[160:161]
	ds_write_b64 v214, v[162:163] offset:32
	ds_write_b64 v214, v[164:165] offset:64
	ds_write_b64 v214, v[166:167] offset:96
	s_waitcnt lgkmcnt(0)
	ds_read_b128 v[144:147], v215
	ds_read_b128 v[148:151], v215 offset:1152
	s_waitcnt lgkmcnt(0)
	global_store_dwordx4 v195, v[144:147], s[68:69]
	global_store_dwordx4 v220, v[148:151], s[68:69]
	v_pk_mul_f32 v[80:81], v[80:81], v[204:205]
	v_pk_mul_f32 v[82:83], v[82:83], v[204:205]
	v_pk_mul_f32 v[84:85], v[84:85], v[204:205]
	v_pk_mul_f32 v[86:87], v[86:87], v[204:205]
	v_pk_mul_f32 v[88:89], v[88:89], v[204:205]
	v_pk_mul_f32 v[90:91], v[90:91], v[204:205]
	v_pk_mul_f32 v[92:93], v[92:93], v[204:205]
	v_pk_mul_f32 v[94:95], v[94:95], v[204:205]
	v_pk_mul_f32 v[96:97], v[96:97], v[204:205]
	v_pk_mul_f32 v[98:99], v[98:99], v[204:205]
	v_pk_mul_f32 v[100:101], v[100:101], v[204:205]
	v_pk_mul_f32 v[102:103], v[102:103], v[204:205]
	v_pk_mul_f32 v[104:105], v[104:105], v[204:205]
	v_pk_mul_f32 v[106:107], v[106:107], v[204:205]
	v_pk_mul_f32 v[108:109], v[108:109], v[204:205]
	v_pk_mul_f32 v[110:111], v[110:111], v[204:205]
	ds_read_b128 v[144:147], v197 offset:0
	ds_read_b128 v[148:151], v197 offset:4352
	ds_read_b128 v[152:155], v197 offset:8704
	ds_read_b128 v[156:159], v197 offset:13056
	ds_read_b128 v[160:163], v197 offset:64
	ds_read_b128 v[164:167], v197 offset:4416
	ds_read_b128 v[168:171], v197 offset:8768
	s_waitcnt lgkmcnt(6)
	s_waitcnt vmcnt(22)
	v_mfma_f32_16x16x32_bf16 v[80:83], v[48:51], v[144:147], v[80:83]
	v_mfma_f32_16x16x32_bf16 v[96:99], v[64:67], v[144:147], v[96:99]
	ds_read_b128 v[172:175], v197 offset:13120
	s_waitcnt lgkmcnt(6)
	v_mfma_f32_16x16x32_bf16 v[84:87], v[48:51], v[148:151], v[84:87]
	v_mfma_f32_16x16x32_bf16 v[100:103], v[64:67], v[148:151], v[100:103]
	ds_read_b128 v[144:147], v197 offset:128
	s_waitcnt lgkmcnt(6)
	v_mfma_f32_16x16x32_bf16 v[88:91], v[48:51], v[152:155], v[88:91]
	v_mfma_f32_16x16x32_bf16 v[104:107], v[64:67], v[152:155], v[104:107]
	ds_read_b128 v[148:151], v197 offset:4480
	s_waitcnt lgkmcnt(6)
	v_mfma_f32_16x16x32_bf16 v[92:95], v[48:51], v[156:159], v[92:95]
	v_mfma_f32_16x16x32_bf16 v[108:111], v[64:67], v[156:159], v[108:111]
	global_load_dwordx4 v[48:51], v192, s[64:65] offset:-4096
	global_load_dwordx4 v[64:67], v192, s[64:65]
	ds_read_b128 v[152:155], v197 offset:8832
	s_waitcnt lgkmcnt(6)
	s_waitcnt vmcnt(22)
	v_mfma_f32_16x16x32_bf16 v[80:83], v[52:55], v[160:163], v[80:83]
	v_mfma_f32_16x16x32_bf16 v[96:99], v[68:71], v[160:163], v[96:99]
	ds_read_b128 v[156:159], v197 offset:13184
	s_waitcnt lgkmcnt(6)
	v_mfma_f32_16x16x32_bf16 v[84:87], v[52:55], v[164:167], v[84:87]
	v_mfma_f32_16x16x32_bf16 v[100:103], v[68:71], v[164:167], v[100:103]
	ds_read_b128 v[160:163], v197 offset:192
	s_waitcnt lgkmcnt(6)
	v_mfma_f32_16x16x32_bf16 v[88:91], v[52:55], v[168:171], v[88:91]
	v_mfma_f32_16x16x32_bf16 v[104:107], v[68:71], v[168:171], v[104:107]
	ds_read_b128 v[164:167], v197 offset:4544
	s_waitcnt lgkmcnt(6)
	v_mfma_f32_16x16x32_bf16 v[92:95], v[52:55], v[172:175], v[92:95]
	v_mfma_f32_16x16x32_bf16 v[108:111], v[68:71], v[172:175], v[108:111]
	global_load_dwordx4 v[52:55], v192, s[64:65] offset:-3072
	global_load_dwordx4 v[68:71], v192, s[64:65] offset:1024
	ds_read_b128 v[168:171], v197 offset:8896
	s_waitcnt lgkmcnt(6)
	s_waitcnt vmcnt(22)
	v_mfma_f32_16x16x32_bf16 v[80:83], v[56:59], v[144:147], v[80:83]
	v_mfma_f32_16x16x32_bf16 v[96:99], v[72:75], v[144:147], v[96:99]
	ds_read_b128 v[172:175], v197 offset:13248
	s_waitcnt lgkmcnt(6)
	v_mfma_f32_16x16x32_bf16 v[84:87], v[56:59], v[148:151], v[84:87]
	v_mfma_f32_16x16x32_bf16 v[100:103], v[72:75], v[148:151], v[100:103]
	s_waitcnt lgkmcnt(5)
	v_mfma_f32_16x16x32_bf16 v[88:91], v[56:59], v[152:155], v[88:91]
	v_mfma_f32_16x16x32_bf16 v[104:107], v[72:75], v[152:155], v[104:107]
	s_waitcnt lgkmcnt(4)
	v_mfma_f32_16x16x32_bf16 v[92:95], v[56:59], v[156:159], v[92:95]
	v_mfma_f32_16x16x32_bf16 v[108:111], v[72:75], v[156:159], v[108:111]
	global_load_dwordx4 v[56:59], v192, s[64:65] offset:-2048
	global_load_dwordx4 v[72:75], v192, s[64:65] offset:2048
	s_waitcnt lgkmcnt(3)
	s_waitcnt vmcnt(22)
	v_mfma_f32_16x16x32_bf16 v[80:83], v[60:63], v[160:163], v[80:83]
	v_mfma_f32_16x16x32_bf16 v[96:99], v[76:79], v[160:163], v[96:99]
	s_waitcnt lgkmcnt(2)
	v_mfma_f32_16x16x32_bf16 v[84:87], v[60:63], v[164:167], v[84:87]
	v_mfma_f32_16x16x32_bf16 v[100:103], v[76:79], v[164:167], v[100:103]
	s_waitcnt lgkmcnt(1)
	v_mfma_f32_16x16x32_bf16 v[88:91], v[60:63], v[168:171], v[88:91]
	v_mfma_f32_16x16x32_bf16 v[104:107], v[76:79], v[168:171], v[104:107]
	s_waitcnt lgkmcnt(0)
	v_mfma_f32_16x16x32_bf16 v[92:95], v[60:63], v[172:175], v[92:95]
	v_mfma_f32_16x16x32_bf16 v[108:111], v[76:79], v[172:175], v[108:111]
	global_load_dwordx4 v[60:63], v192, s[64:65] offset:-1024
	global_load_dwordx4 v[76:79], v192, s[64:65] offset:3072
	s_nop 7
	v_cvt_pk_bf16_f32 v144, v80, v81
	v_cvt_pk_bf16_f32 v145, v82, v83
	ds_write_b64 v200, v[144:145] offset:0
	v_cvt_pk_bf16_f32 v148, v84, v85
	v_cvt_pk_bf16_f32 v149, v86, v87
	ds_write_b64 v200, v[148:149] offset:8448
	v_cvt_pk_bf16_f32 v152, v88, v89
	v_cvt_pk_bf16_f32 v153, v90, v91
	ds_write_b64 v200, v[152:153] offset:16896
	v_cvt_pk_bf16_f32 v156, v92, v93
	v_cvt_pk_bf16_f32 v157, v94, v95
	ds_write_b64 v200, v[156:157] offset:25344
	v_cvt_pk_bf16_f32 v160, v96, v97
	v_cvt_pk_bf16_f32 v161, v98, v99
	ds_write_b64 v200, v[160:161] offset:32
	v_cvt_pk_bf16_f32 v164, v100, v101
	v_cvt_pk_bf16_f32 v165, v102, v103
	ds_write_b64 v200, v[164:165] offset:8480
	v_cvt_pk_bf16_f32 v168, v104, v105
	v_cvt_pk_bf16_f32 v169, v106, v107
	ds_write_b64 v200, v[168:169] offset:16928
	v_cvt_pk_bf16_f32 v172, v108, v109
	v_cvt_pk_bf16_f32 v173, v110, v111
	ds_write_b64 v200, v[172:173] offset:25376
	s_waitcnt vmcnt(46)
	ds_write_b128 v201, v[176:179]
	ds_write_b128 v201, v[180:183] offset:128
	v_add_u32_e32 v196, s80, v196
	v_subrev_u32_e32 v200, s80, v200
	v_add_u32_e32 v197, s81, v197
	v_subrev_u32_e32 v201, s81, v201
	s_sub_u32 s80, 0, s80
	s_sub_u32 s81, 0, s81
	s_add_u32 s68, s68, 0x80000
	s_addc_u32 s69, s69, 0
	s_add_u32 s70, s70, 1
	s_cmp_lt_u32 s70, 31
	s_cselect_b32 s83, 1, 0
	s_lshl_b32 s76, s83, 16
	s_add_u32 s64, s64, s76
	s_addc_u32 s65, s65, 0
	s_cmp_lt_u32 s70, 30
	s_cselect_b32 s83, 1, 0
	s_lshl_b32 s76, s83, 18
	s_add_u32 s60, s60, s76
	s_addc_u32 s61, s61, 0
	s_lshl_b32 s76, s83, 15
	s_add_u32 s62, s62, s76
	s_addc_u32 s63, s63, 0
	s_lshl_b32 s76, s83, 8
	s_add_u32 s66, s66, s76
	s_addc_u32 s67, s67, 0
	s_waitcnt lgkmcnt(0)
	s_barrier
	s_cmp_lt_u32 s70, 32
	s_cbranch_scc1 .Lscan_chunk
	s_waitcnt vmcnt(0)
	global_store_dword v206, v80, s[44:45]
	global_store_dword v207, v81, s[44:45]
	global_store_dword v208, v82, s[44:45]
	global_store_dword v209, v83, s[44:45]
	global_store_dword v206, v84, s[44:45] offset:64
	global_store_dword v207, v85, s[44:45] offset:64
	global_store_dword v208, v86, s[44:45] offset:64
	global_store_dword v209, v87, s[44:45] offset:64
	global_store_dword v206, v88, s[44:45] offset:128
	global_store_dword v207, v89, s[44:45] offset:128
	global_store_dword v208, v90, s[44:45] offset:128
	global_store_dword v209, v91, s[44:45] offset:128
	global_store_dword v206, v92, s[44:45] offset:192
	global_store_dword v207, v93, s[44:45] offset:192
	global_store_dword v208, v94, s[44:45] offset:192
	global_store_dword v209, v95, s[44:45] offset:192
	global_store_dword v206, v96, s[46:47]
	global_store_dword v207, v97, s[46:47]
	global_store_dword v208, v98, s[46:47]
	global_store_dword v209, v99, s[46:47]
	global_store_dword v206, v100, s[46:47] offset:64
	global_store_dword v207, v101, s[46:47] offset:64
	global_store_dword v208, v102, s[46:47] offset:64
	global_store_dword v209, v103, s[46:47] offset:64
	global_store_dword v206, v104, s[46:47] offset:128
	global_store_dword v207, v105, s[46:47] offset:128
	global_store_dword v208, v106, s[46:47] offset:128
	global_store_dword v209, v107, s[46:47] offset:128
	global_store_dword v206, v108, s[46:47] offset:192
	global_store_dword v207, v109, s[46:47] offset:192
	global_store_dword v208, v110, s[46:47] offset:192
	global_store_dword v209, v111, s[46:47] offset:192
